# diff-attention pass prologue: tile 0/1 staging loads hoisted behind the Q loads (overlapped latencies); dtype header comment
# speedup vs baseline: 1.0888x; 1.0013x over previous
; __device__ __forceinline__ float bf2f(unsigned short b) { return __uint_as_float((unsigned)b << 16); }
; template <int DV>
; __device__ __forceinline__ void attn_pass(const int tid, unsigned char* smem, const bf16_t* Q0, int qpitch, const bf16_t* Kb, int kpitch, const bf16_t* Vb, int vpitch,
;                                           int b, int ntiles, float kmax, f32x16 (&o)[DV / 32], float& linv) {
;     ...
;     const int lane = tid & 63, wid = __builtin_amdgcn_readfirstlane(tid >> 6), r32 = lane & 31, hi = lane >> 5;
;     bf16x8 qf[4];
;     { const bf16_t* qp = Q0 + (size_t)(wid * 32 + r32) * qpitch + 8 * hi;
; #pragma unroll
;       for (int ds = 0; ds < 4; ++ds) qf[ds] = *(const bf16x8*)(qp + 16 * ds); }
;     float ssq = 0.f;
; #pragma unroll
;     for (int ds = 0; ds < 4; ++ds)
; #pragma unroll
;         for (int j = 0; j < 8; ++j) { const float f = bf2f((unsigned short)qf[ds][j]); ssq += f * f; }
;     ssq = sum_x32(ssq);
;     const float nshift = -sqrtf(ssq) * kmax;
; #pragma unroll
;     for (int d0 = 0; d0 < DV / 32; ++d0)
; #pragma unroll
;         for (int r = 0; r < 16; ++r) o[d0][r] = 0.f;
;     float lsum = 0.f;
;     const int krow = tid >> 3, kch = tid & 7;
;     u32x4 kreg, vreg[NV];
;     auto tile_row = [&](int kt) -> size_t { return kt < 4 ? (size_t)(NLAT + 256 * b + 64 * kt) : (size_t)(SEQ * b + 64 * (kt - 4)); };
;     auto gload = [&](int kt) {
;         const size_t rb = tile_row(kt);
;         kreg = *(const u32x4*)(Kb + (rb + krow) * kpitch + 8 * kch);
; #pragma unroll
;         for (int i = 0; i < NV; ++i) { const int item = tid + 512 * i; const int vr = (DV == 64) ? (item >> 3) : (item >> 4), vc = (DV == 64) ? (item & 7) : (item & 15);
;             vreg[i] = *(const u32x4*)(Vb + (rb + vr) * vpitch + 8 * vc); }
;     };
;     auto lwrite = [&](int buf) {
;         unsigned char* Ks = smem + buf * BUF; unsigned char* Vs = Ks + KBYTES;
;         *(u32x4*)(Ks + krow * KP + 16 * kch) = kreg;
; #pragma unroll
;         for (int i = 0; i < NV; ++i) { const int item = tid + 512 * i; const int vr = (DV == 64) ? (item >> 3) : (item >> 4), vc = (DV == 64) ? (item & 7) : (item & 15);
;             *(u32x4*)(Vs + vr * VP + 16 * vc) = vreg[i]; }
;     };
;     gload(0); lwrite(0); __syncthreads();
.LBB0_405:
	s_xor_b64 s[14:15], s[16:17], -1
	s_lshl_b64 s[0:1], s[0:1], 1
	s_add_u32 s2, s28, s0
	s_addc_u32 s3, s29, s1
	s_add_u32 s16, s30, s0
	v_readfirstlane_b32 s0, v197
	s_addc_u32 s17, s31, s1
	s_ashr_i32 s0, s0, 1
	s_andn2_b32 s0, s0, 31
	v_or_b32_e32 v0, s0, v218
	v_ashrrev_i32_e32 v1, 31, v0
	v_lshlrev_b64 v[0:1], 11, v[0:1]
	v_lshl_add_u64 v[0:1], s[2:3], 0, v[0:1]
	v_lshl_add_u64 v[0:1], v[0:1], 0, v[192:193]
	global_load_dwordx4 v[96:99], v[0:1], off
	global_load_dwordx4 v[100:103], v[0:1], off offset:32
	global_load_dwordx4 v[104:107], v[0:1], off offset:64
	global_load_dwordx4 v[108:111], v[0:1], off offset:96
	s_mov_b32 s0, 0xf800000
	v_mov_b32_e32 v169, v193
	v_readlane_b32 s68, v251, 29
	v_readlane_b32 s69, v251, 30
	s_lshl_b32 s2, s26, 8
	s_add_u32 s68, s68, s2
	s_addc_u32 s69, s69, 0
	s_mov_b64 s[66:67], s[16:17]
	s_lshl_b32 s2, s10, 8
	s_add_i32 s65, s2, 0x8000
	s_lshl_b32 s2, s10, 13
	s_add_i32 s32, s2, 0xffffff00
	v_lshl_add_u32 v166, v136, 10, v168
	v_lshl_add_u32 v167, v134, 10, v140
	v_lshl_add_u32 v132, v144, 10, v140
	s_mov_b32 s70, 0
	s_cmp_lt_u32 s70, 4
	s_cselect_b32 s2, s65, s32
	s_lshl_b32 s3, s70, 6
	s_add_i32 s2, s2, s3
	s_lshl_b32 s2, s2, 10
	s_add_u32 s60, s66, s2
	s_addc_u32 s61, s67, 0
	s_cmp_lt_u32 s70, 4
	s_cselect_b32 s2, s65, s32
	s_lshl_b32 s3, s70, 6
	s_add_i32 s2, s2, s3
	s_lshl_b32 s2, s2, 10
	s_add_u32 s62, s68, s2
	s_addc_u32 s63, s69, 0
	global_load_dwordx4 v[234:237], v166, s[60:61]
	global_load_dwordx4 v[128:131], v167, s[62:63]
	global_load_dwordx4 v[170:173], v132, s[62:63]
	s_mov_b32 s70, 1
	s_cmp_lt_u32 s70, 4
	s_cselect_b32 s2, s65, s32
	s_lshl_b32 s3, s70, 6
	s_add_i32 s2, s2, s3
	s_lshl_b32 s2, s2, 10
	s_add_u32 s60, s66, s2
	s_addc_u32 s61, s67, 0
	global_load_dwordx4 v[198:201], v166, s[60:61]
	v_mov_b32_e32 v63, v193
	s_waitcnt vmcnt(3)
	v_and_b32_e32 v1, 0xffff0000, v96
	v_lshlrev_b32_e32 v0, 16, v96
	v_mul_f32_e32 v2, v1, v1
	v_fmac_f32_e32 v2, v0, v0
	v_lshlrev_b32_e32 v0, 16, v97
	v_fmac_f32_e32 v2, v0, v0
	v_and_b32_e32 v0, 0xffff0000, v97
	v_fmac_f32_e32 v2, v0, v0
	v_lshlrev_b32_e32 v0, 16, v98
	v_fmac_f32_e32 v2, v0, v0
	v_and_b32_e32 v0, 0xffff0000, v98
	v_fmac_f32_e32 v2, v0, v0
	v_lshlrev_b32_e32 v0, 16, v99
	v_fmac_f32_e32 v2, v0, v0
	v_and_b32_e32 v0, 0xffff0000, v99
	v_fmac_f32_e32 v2, v0, v0
	s_waitcnt vmcnt(2)
	v_lshlrev_b32_e32 v0, 16, v100
	v_fmac_f32_e32 v2, v0, v0
	v_and_b32_e32 v0, 0xffff0000, v100
	v_fmac_f32_e32 v2, v0, v0
	v_lshlrev_b32_e32 v0, 16, v101
	v_fmac_f32_e32 v2, v0, v0
	v_and_b32_e32 v0, 0xffff0000, v101
	v_fmac_f32_e32 v2, v0, v0
	v_lshlrev_b32_e32 v0, 16, v102
	v_fmac_f32_e32 v2, v0, v0
	v_and_b32_e32 v0, 0xffff0000, v102
	v_fmac_f32_e32 v2, v0, v0
	v_lshlrev_b32_e32 v0, 16, v103
	v_fmac_f32_e32 v2, v0, v0
	v_and_b32_e32 v0, 0xffff0000, v103
	v_fmac_f32_e32 v2, v0, v0
	s_waitcnt vmcnt(1)
	v_lshlrev_b32_e32 v0, 16, v104
	v_fmac_f32_e32 v2, v0, v0
	v_and_b32_e32 v0, 0xffff0000, v104
	v_fmac_f32_e32 v2, v0, v0
	v_lshlrev_b32_e32 v0, 16, v105
	v_fmac_f32_e32 v2, v0, v0
	v_and_b32_e32 v0, 0xffff0000, v105
	v_fmac_f32_e32 v2, v0, v0
	v_lshlrev_b32_e32 v0, 16, v106
	v_fmac_f32_e32 v2, v0, v0
	v_and_b32_e32 v0, 0xffff0000, v106
	v_fmac_f32_e32 v2, v0, v0
	v_lshlrev_b32_e32 v0, 16, v107
	v_fmac_f32_e32 v2, v0, v0
	v_and_b32_e32 v0, 0xffff0000, v107
	v_fmac_f32_e32 v2, v0, v0
	s_waitcnt vmcnt(0)
	v_lshlrev_b32_e32 v0, 16, v108
	v_fmac_f32_e32 v2, v0, v0
	v_and_b32_e32 v0, 0xffff0000, v108
	v_fmac_f32_e32 v2, v0, v0
	v_lshlrev_b32_e32 v0, 16, v109
	v_fmac_f32_e32 v2, v0, v0
	v_and_b32_e32 v0, 0xffff0000, v109
	v_fmac_f32_e32 v2, v0, v0
	v_and_b32_e32 v1, 0xffff0000, v110
	v_lshlrev_b32_e32 v0, 16, v110
	v_pk_mul_f32 v[0:1], v[0:1], v[0:1]
	s_nop 0
	v_add_f32_e32 v0, v0, v2
	v_add_f32_e32 v2, v1, v0
	v_and_b32_e32 v1, 0xffff0000, v111
	v_lshlrev_b32_e32 v0, 16, v111
	v_pk_mul_f32 v[0:1], v[0:1], v[0:1]
	s_nop 0
	v_add_f32_e32 v0, v0, v2
	v_add_f32_e32 v0, v1, v0
	v_mov_b32_e32 v1, v0
	s_nop 1
	v_permlane32_swap_b32_e32 v0, v1
	v_add_f32_e32 v0, v0, v1
	v_cmp_gt_f32_e32 vcc, s0, v0
	v_mul_f32_e32 v1, 0x4f800000, v0
	s_nop 0
	v_cndmask_b32_e32 v0, v0, v1, vcc
	v_sqrt_f32_e32 v1, v0
	s_nop 0
	v_add_u32_e32 v2, -1, v1
	v_fma_f32 v3, -v2, v1, v0
	v_cmp_ge_f32_e64 s[0:1], 0, v3
	v_add_u32_e32 v3, 1, v1
	s_nop 0
	v_cndmask_b32_e64 v2, v1, v2, s[0:1]
	v_fma_f32 v1, -v3, v1, v0
	v_cmp_lt_f32_e64 s[0:1], 0, v1
	s_nop 1
	v_cndmask_b32_e64 v1, v2, v3, s[0:1]
	v_mul_f32_e32 v2, 0x37800000, v1
	v_cndmask_b32_e32 v1, v1, v2, vcc
	v_cmp_class_f32_e32 vcc, v0, v227
	s_nop 1
	v_cndmask_b32_e32 v0, v1, v0, vcc
	v_mul_f32_e64 v32, v214, -v0
	v_mov_b32_e32 v33, v32
	v_mov_b32_e32 v34, v32
	v_mov_b32_e32 v35, v32
	v_mov_b32_e32 v36, v32
	v_mov_b32_e32 v37, v32
	v_mov_b32_e32 v38, v32
	v_mov_b32_e32 v39, v32
	v_mov_b32_e32 v40, v32
	v_mov_b32_e32 v41, v32
	v_mov_b32_e32 v42, v32
	v_mov_b32_e32 v43, v32
	v_mov_b32_e32 v44, v32
	v_mov_b32_e32 v45, v32
	v_mov_b32_e32 v46, v32
	v_mov_b32_e32 v47, v32
	v_mov_b32_e32 v0, 0
	v_mov_b32_e32 v1, 0
	v_mov_b32_e32 v2, 0
	v_mov_b32_e32 v3, 0
	v_mov_b32_e32 v4, 0
	v_mov_b32_e32 v5, 0
	v_mov_b32_e32 v6, 0
	v_mov_b32_e32 v7, 0
	v_mov_b32_e32 v8, 0
	v_mov_b32_e32 v9, 0
	v_mov_b32_e32 v10, 0
	v_mov_b32_e32 v11, 0
	v_mov_b32_e32 v12, 0
	v_mov_b32_e32 v13, 0
	v_mov_b32_e32 v14, 0
	v_mov_b32_e32 v15, 0
	v_mov_b32_e32 v16, 0
	v_mov_b32_e32 v17, 0
	v_mov_b32_e32 v18, 0
	v_mov_b32_e32 v19, 0
	v_mov_b32_e32 v20, 0
	v_mov_b32_e32 v21, 0
	v_mov_b32_e32 v22, 0
	v_mov_b32_e32 v23, 0
	v_mov_b32_e32 v24, 0
	v_mov_b32_e32 v25, 0
	v_mov_b32_e32 v26, 0
	v_mov_b32_e32 v27, 0
	v_mov_b32_e32 v28, 0
	v_mov_b32_e32 v29, 0
	v_mov_b32_e32 v30, 0
	v_mov_b32_e32 v31, 0
	v_mov_b32_e32 v48, 0
	v_mov_b32_e32 v49, 0
	v_mov_b32_e32 v50, 0
	v_mov_b32_e32 v51, 0
	v_mov_b32_e32 v52, 0
	v_mov_b32_e32 v53, 0
	v_mov_b32_e32 v54, 0
	v_mov_b32_e32 v55, 0
	v_mov_b32_e32 v56, 0
	v_mov_b32_e32 v57, 0
	v_mov_b32_e32 v58, 0
	v_mov_b32_e32 v59, 0
	v_mov_b32_e32 v60, 0
	v_mov_b32_e32 v61, 0
	v_mov_b32_e32 v62, 0
	v_mov_b32_e32 v63, 0
	v_mov_b32_e32 v64, 0
	v_mov_b32_e32 v65, 0
	v_mov_b32_e32 v66, 0
	v_mov_b32_e32 v67, 0
	v_mov_b32_e32 v68, 0
	v_mov_b32_e32 v69, 0
	v_mov_b32_e32 v70, 0
	v_mov_b32_e32 v71, 0
	v_mov_b32_e32 v72, 0
	v_mov_b32_e32 v73, 0
	v_mov_b32_e32 v74, 0
	v_mov_b32_e32 v75, 0
	v_mov_b32_e32 v76, 0
	v_mov_b32_e32 v77, 0
	v_mov_b32_e32 v78, 0
	v_mov_b32_e32 v79, 0
	v_mov_b32_e32 v169, 0
	v_add_u32_e32 v248, v212, v139
	v_add_u32_e32 v249, v219, v140
	v_add_u32_e32 v133, v220, v140
	s_waitcnt vmcnt(0)
	ds_write_b128 v248, v[234:237]
	ds_write_b128 v248, v[198:201] offset:29696
	ds_write_b128 v249, v[128:131] offset:38912
	ds_write_b128 v133, v[170:173] offset:38912
	s_waitcnt lgkmcnt(0)
	s_barrier
; template <int DV>
; __device__ __forceinline__ void attn_pass(const int tid, unsigned char* smem, const bf16_t* Q0, int qpitch, const bf16_t* Kb, int kpitch, const bf16_t* Vb, int vpitch,
;                                           int b, int ntiles, float kmax, f32x16 (&o)[DV / 32], float& linv) {
;     ...
;     gload(0); lwrite(0); __syncthreads();
;     const int nhalf = (lane >> 4) & 1, q4 = (lane & 15) >> 2, p4 = lane & 3;
;     for (int kt = 0; kt < ntiles; ++kt) {
;         if (kt + 1 < ntiles) gload(kt + 1);
;         const unsigned char* Ks = smem + (kt & 1) * BUF; const unsigned char* Vs = Ks + KBYTES;
;         const unsigned char* kp = Ks + r32 * KP + hi * 16;
;         bf16x8 pf[2][2];
; #pragma unroll
;         for (int kb = 0; kb < 2; ++kb) {
;             f32x16 s;
; #pragma unroll
;             for (int r = 0; r < 16; ++r) s[r] = nshift;
; #pragma unroll
;             for (int ds = 0; ds < 4; ++ds) {
;                 const bf16x8 kf = *(const bf16x8*)(kp + kb * 32 * KP + ds * 32);
;                 s = __builtin_amdgcn_mfma_f32_32x32x16_bf16(kf, qf[ds], s, 0, 0, 0);
;             }
;             float ls = 0.f;
; #pragma unroll
;             for (int r = 0; r < 16; ++r) { s[r] = __builtin_amdgcn_exp2f(s[r]); ls += s[r]; }
;             lsum += ls;
; #pragma unroll
;             for (int j = 0; j < 2; ++j) {
;                 u32x4 w0;
;                 w0.x = cvt_pk_bf16(s[8 * j + 0], s[8 * j + 1]); w0.y = cvt_pk_bf16(s[8 * j + 2], s[8 * j + 3]); w0.z = cvt_pk_bf16(s[8 * j + 4], s[8 * j + 5]); w0.w = cvt_pk_bf16(s[8 * j + 6], s[8 * j + 7]);
;                 pf[kb][j] = __builtin_bit_cast(bf16x8, w0);
;             }
;         }
;         const unsigned char* vp = Vs + (4 * hi + q4) * VP + (16 * nhalf + 4 * p4) * 2;
; #pragma unroll
;         for (int d0 = 0; d0 < DV / 32; ++d0) {
; #pragma unroll
;             for (int kb = 0; kb < 2; ++kb)
; #pragma unroll
;                 for (int j = 0; j < 2; ++j) {
;                     const unsigned char* a = vp + (32 * kb + 16 * j) * VP + d0 * 64;
;                     const s16x4 lo = ld_tr(a), h4 = ld_tr(a + 8 * VP);
;                     const bf16x8 vf = (bf16x8){lo[0], lo[1], lo[2], lo[3], h4[0], h4[1], h4[2], h4[3]};
;                     o[d0] = __builtin_amdgcn_mfma_f32_32x32x16_bf16(vf, pf[kb][j], o[d0], 0, 0, 0);
;                 }
;             if (d0 & 1) __builtin_amdgcn_sched_barrier(0);
	s_mov_b32 s56, 0
	s_movk_i32 s57, 0x7400
	s_mov_b32 s58, 0xe800
	s_mov_b32 s59, 0
	s_add_i32 s71, s25, -1
	s_add_i32 s70, s59, 2
	s_min_u32 s70, s70, s71
	s_cmp_lt_u32 s70, 4
	s_cselect_b32 s2, s65, s32
	s_lshl_b32 s3, s70, 6
	s_add_i32 s2, s2, s3
	s_lshl_b32 s2, s2, 10
	s_add_u32 s60, s66, s2
	s_addc_u32 s61, s67, 0
	s_add_i32 s70, s59, 1
	s_min_u32 s70, s70, s71
	s_cmp_lt_u32 s70, 4
	s_cselect_b32 s2, s65, s32
	s_lshl_b32 s3, s70, 6
	s_add_i32 s2, s2, s3
	s_lshl_b32 s2, s2, 10
	s_add_u32 s62, s68, s2
	s_addc_u32 s63, s69, 0
	global_load_dwordx4 v[234:237], v166, s[60:61]
	global_load_dwordx4 v[128:131], v167, s[62:63]
	global_load_dwordx4 v[170:173], v132, s[62:63]
	v_add_u32_e32 v174, v213, v138
	ds_read_b128 v[198:201], v174 offset:0
	ds_read_b128 v[202:205], v174 offset:32
	ds_read_b128 v[206:209], v174 offset:64
	ds_read_b128 v[150:153], v174 offset:96
	v_add3_u32 v174, s56, v213, v138
	v_add3_u32 v175, s56, v141, v221
	v_add3_u32 v210, s57, v213, v138
	v_add3_u32 v211, s57, v141, v221
	s_waitcnt lgkmcnt(3)
	v_mfma_f32_32x32x16_bf16 v[80:95], v[198:201], v[96:99], v[32:47]
	ds_read_b128 v[198:201], v174 offset:4608
	v_add3_u32 v248, s58, v212, v139
	v_add3_u32 v249, s58, v219, v140
	v_add3_u32 v133, s58, v220, v140
	s_waitcnt vmcnt(0)
	ds_write_b128 v248, v[234:237]
	ds_write_b128 v249, v[128:131] offset:9216
	ds_write_b128 v133, v[170:173] offset:9216
	s_waitcnt lgkmcnt(6)
	v_mfma_f32_32x32x16_bf16 v[80:95], v[202:205], v[100:103], v[80:95]
	ds_read_b128 v[202:205], v174 offset:4640
	s_add_i32 s71, s25, -1
	s_add_i32 s70, s59, 3
	s_min_u32 s70, s70, s71
	s_cmp_lt_u32 s70, 4
	s_cselect_b32 s2, s65, s32
	s_lshl_b32 s3, s70, 6
	s_add_i32 s2, s2, s3
	s_lshl_b32 s2, s2, 10
	s_add_u32 s60, s66, s2
	s_addc_u32 s61, s67, 0
	s_add_i32 s70, s59, 2
	s_min_u32 s70, s70, s71
	s_cmp_lt_u32 s70, 4
	s_cselect_b32 s2, s65, s32
	s_lshl_b32 s3, s70, 6
	s_add_i32 s2, s2, s3
	s_lshl_b32 s2, s2, 10
	s_add_u32 s62, s68, s2
	s_addc_u32 s63, s69, 0
	s_waitcnt lgkmcnt(6)
	v_mfma_f32_32x32x16_bf16 v[80:95], v[206:209], v[104:107], v[80:95]
	ds_read_b128 v[206:209], v174 offset:4672
	global_load_dwordx4 v[234:237], v166, s[60:61]
	global_load_dwordx4 v[128:131], v167, s[62:63]
	global_load_dwordx4 v[170:173], v132, s[62:63]
	s_waitcnt lgkmcnt(6)
	v_mfma_f32_32x32x16_bf16 v[80:95], v[150:153], v[108:111], v[80:95]
	ds_read_b128 v[150:153], v174 offset:4704
	s_nop 7
	s_waitcnt lgkmcnt(6)
	v_mfma_f32_32x32x16_bf16 v[112:127], v[198:201], v[96:99], v[32:47]
	ds_read_b128 v[198:201], v210 offset:0
	ds_read_b64_tr_b16 v[154:155], v211 offset:9216
	ds_read_b64_tr_b16 v[156:157], v211 offset:11776
	v_exp_f32_e32 v80, v80
	v_exp_f32_e32 v81, v81
	v_exp_f32_e32 v82, v82
	v_add_f32_e32 v169, v169, v80
	v_exp_f32_e32 v83, v83
	v_add_f32_e32 v169, v169, v81
	v_cvt_pk_bf16_f32 v176, v80, v81
	v_exp_f32_e32 v84, v84
	v_add_f32_e32 v169, v169, v82
	v_exp_f32_e32 v85, v85
	v_add_f32_e32 v169, v169, v83
	v_cvt_pk_bf16_f32 v177, v82, v83
	v_exp_f32_e32 v86, v86
	s_waitcnt lgkmcnt(5)
	v_mfma_f32_32x32x16_bf16 v[112:127], v[202:205], v[100:103], v[112:127]
	ds_read_b128 v[202:205], v210 offset:32
	ds_read_b64_tr_b16 v[158:159], v211 offset:9280
	ds_read_b64_tr_b16 v[160:161], v211 offset:11840
	v_add_f32_e32 v169, v169, v84
	v_exp_f32_e32 v87, v87
	v_add_f32_e32 v169, v169, v85
	v_cvt_pk_bf16_f32 v178, v84, v85
	v_exp_f32_e32 v88, v88
	v_add_f32_e32 v169, v169, v86
	v_exp_f32_e32 v89, v89
	v_add_f32_e32 v169, v169, v87
	v_cvt_pk_bf16_f32 v179, v86, v87
	v_exp_f32_e32 v90, v90
	v_add_f32_e32 v169, v169, v88
	v_exp_f32_e32 v91, v91
	v_add_f32_e32 v169, v169, v89
	s_waitcnt lgkmcnt(7)
	v_mfma_f32_32x32x16_bf16 v[112:127], v[206:209], v[104:107], v[112:127]
	ds_read_b128 v[206:209], v210 offset:64
	ds_read_b64_tr_b16 v[162:163], v211 offset:9344
	ds_read_b64_tr_b16 v[164:165], v211 offset:11904
	v_cvt_pk_bf16_f32 v180, v88, v89
	v_exp_f32_e32 v92, v92
	v_add_f32_e32 v169, v169, v90
	v_exp_f32_e32 v93, v93
	v_add_f32_e32 v169, v169, v91
	v_cvt_pk_bf16_f32 v181, v90, v91
	v_exp_f32_e32 v94, v94
	v_add_f32_e32 v169, v169, v92
	v_exp_f32_e32 v95, v95
	v_add_f32_e32 v169, v169, v93
	v_cvt_pk_bf16_f32 v182, v92, v93
	v_add_f32_e32 v169, v169, v94
	v_add_f32_e32 v169, v169, v95
	v_cvt_pk_bf16_f32 v183, v94, v95
	s_waitcnt lgkmcnt(9)
	v_mfma_f32_32x32x16_bf16 v[112:127], v[150:153], v[108:111], v[112:127]
	ds_read_b128 v[150:153], v210 offset:96
	ds_read_b64_tr_b16 v[230:231], v211 offset:9408
	ds_read_b64_tr_b16 v[232:233], v211 offset:11968
	v_add3_u32 v142, s57, v213, v138
	v_add3_u32 v143, s57, v141, v221
	v_add3_u32 v146, s58, v213, v138
	v_add3_u32 v147, s58, v141, v221
	s_mov_b32 s2, s56
	s_mov_b32 s56, s57
	s_mov_b32 s57, s58
	s_mov_b32 s58, s2
	s_add_i32 s59, s59, 1
	v_add3_u32 v248, s58, v212, v139
	v_add3_u32 v249, s58, v219, v140
	v_add3_u32 v133, s58, v220, v140
	s_waitcnt lgkmcnt(0)
	s_barrier
